# adds: G1 copy-out V-transpose path rewritten - one row address stepped by scalar multiples of the pitch instead of 8 rebuilt addresses with integer multiplies, 8 LDS reads per store issued together, t
# speedup vs baseline: 1.0497x; 1.0092x over previous
; DI void st_nt16(void* q, uint4 v) { ntu4 t = {v.x, v.y, v.z, v.w}; __builtin_nontemporal_store(t, (ntu4*)q); }
; template <int CT>
; DI void phase_g1(int c, int l) {
;     ...
;       if (sd.kind == 2) {
;         const int dsh = sd.dsh, L = S0 >> dsh;
; #pragma unroll
;         for (int i = 0; i < 4; ++i) {
;           const int idx = etid + i * NTHREADS, dim = idx & 63, cc = idx >> 6;
;           const int r = cc >> (5 - dsh), i8 = cc & ((32 >> dsh) - 1), g16 = i8 >> 1, hh = i8 & 1;
;           unsigned w[4];
; #pragma unroll
;           for (int e2 = 0; e2 < 4; ++e2) {
;             const int ka = g16 * 16 + 8 * (e2 >> 1) + 4 * hh + 2 * (e2 & 1);
;             const int ta = r + (ka << dsh), tb = r + ((ka + 1) << dsh);
;             unsigned lo = *(const u16*)(shm + ta * TP + (seg * 64 + dim) * 2);
;             unsigned hi = *(const u16*)(shm + tb * TP + (seg * 64 + dim) * 2);
;             w[e2] = lo | (hi << 16);
;           }
;           uint4 o; o.x = w[0]; o.y = w[1]; o.z = w[2]; o.w = w[3];
;           const int rowg0 = sl + r * L + (pos0 >> dsh) + g16 * 16;
;           const int blk = rowg0 >> 5, s_ = (rowg0 >> 4) & 1;
;           st_nt16(sd.base + ((((size_t)blk * 2 + (dim >> 5)) * 2 + s_) * 64 + hh * 32 + (dim & 31)) * 8, o);
;         }
.LBB0_549:
	s_lshr_b32 s80, 32, s54
	s_add_i32 s80, s80, -1
	s_sub_i32 s75, 5, s54
	s_lshr_b32 s26, s19, s54
	s_lshr_b32 s27, s22, s54
	s_add_i32 s27, s27, s21
	s_lshl_b32 vcc_lo, s82, s54
	s_mul_i32 vcc_hi, vcc_lo, 5
	s_nop 1
	v_and_b32_e32 v163, s80, v171
	v_lshlrev_b32_e32 v163, 3, v163
	v_and_b32_e32 v163, -16, v163
	v_or_b32_e32 v165, v163, v172
	v_ashrrev_i32_e32 v161, s75, v171
	v_lshl_add_u32 v179, v165, s54, v161
	v_mul_lo_u32 v179, v179, s82
	v_add3_u32 v179, v159, v179, s25
	ds_read_u16 v190, v179
	v_add_u32_e32 v179, vcc_lo, v179
	ds_read_u16 v191, v179
	v_add_u32_e32 v179, vcc_lo, v179
	ds_read_u16 v192, v179
	v_add_u32_e32 v179, vcc_lo, v179
	ds_read_u16 v193, v179
	v_add_u32_e32 v179, vcc_hi, v179
	ds_read_u16 v194, v179
	v_add_u32_e32 v179, vcc_lo, v179
	ds_read_u16 v195, v179
	v_add_u32_e32 v179, vcc_lo, v179
	ds_read_u16 v196, v179
	v_add_u32_e32 v179, vcc_lo, v179
	ds_read_u16 v197, v179
	v_mul_lo_u32 v161, v161, s26
	v_add3_u32 v161, v161, s27, v163
	v_ashrrev_i32_e32 v184, 5, v161
	v_ashrrev_i32_e32 v185, 31, v184
	v_lshrrev_b32_e32 v161, 4, v161
	v_lshlrev_b64 v[184:185], 2, v[184:185]
	v_and_or_b32 v161, v161, 1, v184
	v_or_b32_e32 v184, v161, v6
	v_lshlrev_b64 v[184:185], 10, v[184:185]
	v_lshl_add_u64 v[184:185], s[6:7], 0, v[184:185]
	v_lshl_add_u64 v[184:185], v[184:185], 0, v[150:151]
	v_and_b32_e32 v163, s80, v173
	v_lshlrev_b32_e32 v163, 3, v163
	v_and_b32_e32 v163, -16, v163
	v_or_b32_e32 v165, v163, v174
	v_ashrrev_i32_e32 v161, s75, v173
	v_lshl_add_u32 v179, v165, s54, v161
	v_mul_lo_u32 v179, v179, s82
	v_add3_u32 v179, v159, v179, s25
	ds_read_u16 v198, v179
	v_add_u32_e32 v179, vcc_lo, v179
	ds_read_u16 v199, v179
	v_add_u32_e32 v179, vcc_lo, v179
	ds_read_u16 v200, v179
	v_add_u32_e32 v179, vcc_lo, v179
	ds_read_u16 v201, v179
	v_add_u32_e32 v179, vcc_hi, v179
	ds_read_u16 v202, v179
	v_add_u32_e32 v179, vcc_lo, v179
	ds_read_u16 v203, v179
	v_add_u32_e32 v179, vcc_lo, v179
	ds_read_u16 v204, v179
	v_add_u32_e32 v179, vcc_lo, v179
	ds_read_u16 v205, v179
	v_mul_lo_u32 v161, v161, s26
	v_add3_u32 v161, v161, s27, v163
	v_ashrrev_i32_e32 v186, 5, v161
	v_ashrrev_i32_e32 v187, 31, v186
	v_lshrrev_b32_e32 v161, 4, v161
	v_lshlrev_b64 v[186:187], 2, v[186:187]
	v_and_or_b32 v161, v161, 1, v186
	v_or_b32_e32 v186, v161, v6
	v_lshlrev_b64 v[186:187], 10, v[186:187]
	v_lshl_add_u64 v[186:187], s[6:7], 0, v[186:187]
	v_lshl_add_u64 v[186:187], v[186:187], 0, v[152:153]
	s_waitcnt lgkmcnt(8)
	v_lshl_or_b32 v180, v191, 16, v190
	v_lshl_or_b32 v181, v193, 16, v192
	v_lshl_or_b32 v182, v195, 16, v194
	v_lshl_or_b32 v183, v197, 16, v196
	global_store_dwordx4 v[184:185], v[180:183], off nt
	v_and_b32_e32 v163, s80, v175
	v_lshlrev_b32_e32 v163, 3, v163
	v_and_b32_e32 v163, -16, v163
	v_or_b32_e32 v165, v163, v176
	v_ashrrev_i32_e32 v161, s75, v175
	v_lshl_add_u32 v179, v165, s54, v161
	v_mul_lo_u32 v179, v179, s82
	v_add3_u32 v179, v159, v179, s25
	ds_read_u16 v190, v179
	v_add_u32_e32 v179, vcc_lo, v179
	ds_read_u16 v191, v179
	v_add_u32_e32 v179, vcc_lo, v179
	ds_read_u16 v192, v179
	v_add_u32_e32 v179, vcc_lo, v179
	ds_read_u16 v193, v179
	v_add_u32_e32 v179, vcc_hi, v179
	ds_read_u16 v194, v179
	v_add_u32_e32 v179, vcc_lo, v179
	ds_read_u16 v195, v179
	v_add_u32_e32 v179, vcc_lo, v179
	ds_read_u16 v196, v179
	v_add_u32_e32 v179, vcc_lo, v179
	ds_read_u16 v197, v179
	v_mul_lo_u32 v161, v161, s26
	v_add3_u32 v161, v161, s27, v163
	v_ashrrev_i32_e32 v184, 5, v161
	v_ashrrev_i32_e32 v185, 31, v184
	v_lshrrev_b32_e32 v161, 4, v161
	v_lshlrev_b64 v[184:185], 2, v[184:185]
	v_and_or_b32 v161, v161, 1, v184
	v_or_b32_e32 v184, v161, v6
	v_lshlrev_b64 v[184:185], 10, v[184:185]
	v_lshl_add_u64 v[184:185], s[6:7], 0, v[184:185]
	v_lshl_add_u64 v[184:185], v[184:185], 0, v[154:155]
	s_waitcnt lgkmcnt(8)
	v_lshl_or_b32 v180, v199, 16, v198
	v_lshl_or_b32 v181, v201, 16, v200
	v_lshl_or_b32 v182, v203, 16, v202
	v_lshl_or_b32 v183, v205, 16, v204
	global_store_dwordx4 v[186:187], v[180:183], off nt
	v_and_b32_e32 v163, s80, v177
	v_lshlrev_b32_e32 v163, 3, v163
	v_and_b32_e32 v163, -16, v163
	v_or_b32_e32 v165, v163, v178
	v_ashrrev_i32_e32 v161, s75, v177
	v_lshl_add_u32 v179, v165, s54, v161
	v_mul_lo_u32 v179, v179, s82
	v_add3_u32 v179, v159, v179, s25
	ds_read_u16 v198, v179
	v_add_u32_e32 v179, vcc_lo, v179
	ds_read_u16 v199, v179
	v_add_u32_e32 v179, vcc_lo, v179
	ds_read_u16 v200, v179
	v_add_u32_e32 v179, vcc_lo, v179
	ds_read_u16 v201, v179
	v_add_u32_e32 v179, vcc_hi, v179
	ds_read_u16 v202, v179
	v_add_u32_e32 v179, vcc_lo, v179
	ds_read_u16 v203, v179
	v_add_u32_e32 v179, vcc_lo, v179
	ds_read_u16 v204, v179
	v_add_u32_e32 v179, vcc_lo, v179
	ds_read_u16 v205, v179
	v_mul_lo_u32 v161, v161, s26
	v_add3_u32 v161, v161, s27, v163
	v_ashrrev_i32_e32 v186, 5, v161
	v_ashrrev_i32_e32 v187, 31, v186
	v_lshrrev_b32_e32 v161, 4, v161
	v_lshlrev_b64 v[186:187], 2, v[186:187]
	v_and_or_b32 v161, v161, 1, v186
	v_or_b32_e32 v186, v161, v6
	v_lshlrev_b64 v[186:187], 10, v[186:187]
	v_lshl_add_u64 v[186:187], s[6:7], 0, v[186:187]
	v_lshl_add_u64 v[186:187], v[186:187], 0, v[156:157]
	s_waitcnt lgkmcnt(8)
	v_lshl_or_b32 v180, v191, 16, v190
	v_lshl_or_b32 v181, v193, 16, v192
	v_lshl_or_b32 v182, v195, 16, v194
	v_lshl_or_b32 v183, v197, 16, v196
	global_store_dwordx4 v[184:185], v[180:183], off nt
	s_waitcnt lgkmcnt(0)
	s_nop 1
	v_lshl_or_b32 v180, v199, 16, v198
	v_lshl_or_b32 v181, v201, 16, v200
	v_lshl_or_b32 v182, v203, 16, v202
	v_lshl_or_b32 v183, v205, 16, v204
	global_store_dwordx4 v[186:187], v[180:183], off nt
	s_cbranch_execnz .LBB0_523
	s_branch .LBB0_561

; #define LOAD_PARAMS() KParams kq_ = (KParams)__builtin_amdgcn_kernarg_segment_ptr(); asm volatile("" : "+s"(kq_)); const Params p = *kq_
; template <int CT>
; __global__ void __launch_bounds__(NTHREADS) mega_kernel(Params p) {
;     ...
; #pragma unroll 1
;   for (int ph = 0; ph < nph; ++ph) {
;     run_phase<CT>(ph);
;     if (ph + 1 < nph) {
;       LOAD_PARAMS();
;       xcd_barrier((unsigned*)(p.ws + WS<CT>::bar), x, nloc, nx, k);
;       ++k;
;     }
;   }
; }
.LBB0_726:
	s_endpgm
	s_nop 0
	s_nop 0
	s_nop 0
	s_nop 0
	s_nop 0
	s_nop 0
	s_nop 0
	s_nop 0
	s_nop 0
	s_nop 0
	s_nop 0
	s_nop 0
	s_nop 0
	s_nop 0
	s_nop 0
	s_nop 0
	s_nop 0
	s_nop 0
	s_nop 0
	s_nop 0
	s_nop 0
	s_nop 0
	s_nop 0
	s_nop 0
	s_nop 0
	s_nop 0
	s_nop 0
	s_nop 0
	s_nop 0
	s_nop 0
	s_nop 0
	s_endpgm
